# code placement: mode-A attention code shifted by 4 bytes (one s_nop in an unreachable slot before and after it) so its loop returns to the byte phase it has in the baseline
# speedup vs baseline: 1.0007x; 1.0007x over previous
; #define LAS __attribute__((address_space(3)))
; __device__ __forceinline__ void phase_attn(LAS unsigned char* lds, const AttnCtx& cx) {
;     const int G = gridDim.x, nb = cx.n >> 7;
;     const int c = (G % 8 == 0) ? (int)(blockIdx.x & 7) * (G >> 3) + (int)(blockIdx.x >> 3) : (int)blockIdx.x;
;     const int npb = (cx.row0 < NPROMPT) ? (NPROMPT - cx.row0) >> 7 : 0;
;     for (int rep = 0; rep < (DUP_PH == 20 ? 2 : 1); ++rep)
;     for (int it = c; it < nb * 4; it += G) {
;         int tb, head;
;         if (it < npb * 4) { const int sq = it >> 7, rem = it & 127; head = rem >> 5; tb = sq * 32 + (rem & 31); }
;         else { const int i2 = it - npb * 4, sq = i2 >> 6, rem = i2 & 63; head = rem >> 4; tb = npb + sq * 16 + (rem & 15); }
;         attn_item<64, 128, 0>(lds, tb * 4 + head, cx);
.LBB0_157:
	v_writelane_b32 v255, s8, 26
	s_nop 1
	v_writelane_b32 v255, s9, 27
	s_nop 0
	v_readlane_b32 s0, v255, 22
	s_lshr_b32 s0, s0, 5
	s_cmp_lt_i32 s2, s0
	s_cselect_b64 s[4:5], -1, 0
	v_writelane_b32 v255, s4, 28
	s_cmp_ge_i32 s2, s0
	s_nop 0
	v_writelane_b32 v255, s5, 29
	v_writelane_b32 v255, s0, 30
	s_cbranch_scc1 .LBB0_291
	v_readlane_b32 s3, v255, 24
	s_sub_i32 s0, 0x4000, s3
	s_lshr_b32 s0, s0, 7
	v_readlane_b32 s1, v255, 19
	s_cmp_lt_i32 s1, 5
	s_cselect_b32 s72, s0, 0
	v_readlane_b32 s22, v255, 16
	s_lshl_b32 s73, s72, 2
	v_readlane_b32 s23, v255, 17
	v_readlane_b32 s4, v254, 61
	s_and_b64 s[0:1], s[22:23], exec
	v_readlane_b32 s5, v254, 62
	s_cselect_b32 s0, 0x200, 0
	v_readlane_b32 s16, v255, 9
	v_cndmask_b32_e64 v0, 0, 1, s[22:23]
	v_readlane_b32 s4, v254, 17
	v_readlane_b32 s17, v255, 10
	s_add_u32 s0, s16, s0
	v_lshlrev_b32_e32 v0, 2, v0
	v_readlane_b32 s5, v254, 18
	s_addc_u32 s1, s17, 0
	s_sub_i32 s74, 0, s3
	s_waitcnt vmcnt(0)
	v_lshl_add_u64 v[178:179], s[4:5], 0, v[0:1]
	s_mov_b32 s75, s2
	v_readlane_b32 s6, v254, 63
	v_readlane_b32 s7, v255, 0
	v_readlane_b32 s8, v255, 1
	v_readlane_b32 s9, v255, 2
	v_readlane_b32 s10, v255, 3
	v_readlane_b32 s11, v255, 4
	v_readlane_b32 s12, v255, 5
	v_readlane_b32 s13, v255, 6
	v_readlane_b32 s14, v255, 7
	v_readlane_b32 s15, v255, 8
	v_readlane_b32 s18, v255, 11
	v_readlane_b32 s19, v255, 12
	s_branch .LBB0_160
	s_nop 0

; #define LAS __attribute__((address_space(3)))
; template <int DQK, int DV, int MODE>
; __device__ __forceinline__ void attn_item(LAS unsigned char* lds, int item, const AttnCtx& cx) {
;     ...
;     auto issue = [&](int j) {
;         const int sbase = (j % NST) * SB;
; #pragma unroll
;         for (int i = 0; i < LPWMAX; ++i) {
;             const int cid = wq + 4 * i;
;             if (cid < nchh) {
;                 const bool isv = cid >= KCH; const int lc = isv ? cid - KCH : cid;
;                 const int pc = lc * 64 + lane, ppr = isv ? VP / 16 : KP / 16, row = pc / ppr, cp = pc - row * ppr;
;                 if (cp < (isv ? DV / 8 : DQK / 8)) {
;                     const bf16_t* src = P + (size_t)ktok(j, row) * NIN + (isv ? vcol : kcol) + cp * 8;
;                     __builtin_amdgcn_global_load_lds((const unsigned*)src, (LAS unsigned*)(lds + sbase + (isv ? voff : koff) + lc * 1024), 16, 0, 0);
;                 }
;             }
;         }
;     };
.LBB0_290:
	v_add_u32_e32 v0, 0x80, v27
	v_mad_i64_i32 v[24:25], s[82:83], v0, s33, v[12:13]
	s_lshl_b32 s48, s51, 1
	v_lshl_add_u64 v[24:25], v[24:25], 0, s[48:49]
	s_add_i32 s48, s90, 0
	s_add_i32 m0, s48, 0x17800
	s_nop 0
	global_load_lds_dwordx4 v[24:25], off
	s_or_b64 exec, exec, s[68:69]
	s_and_saveexec_b64 s[68:69], s[62:63]
	s_cbranch_execnz .LBB0_198
	s_branch .LBB0_199
	s_nop 0
